# work redistribution in the scan+kv-up phase: workgroups 0-15 (which run both a sample scan item and a fused prompt scan item) no longer take kv-up GEMM tiles; their 96 tiles go to workgroups 32-127 as
# speedup vs baseline: 1.0868x; 1.0085x over previous
; #define TIDX tid_opaque()
; #define LAUNDER(q) PP q = (PP)__builtin_amdgcn_kernarg_segment_ptr(); asm volatile("" : "+s"(q));
; __global__ void __launch_bounds__(NTHR, 2) fwd_megakernel(Params p0) {
;     ...
;                 for (int rep = 0; rep <= DUP_SCAN; ++rep) {
;                     LAUNDER(p)
;                     const int wave = TIDX >> 6;
;                     float* wl = (float*)smem + wave * 1536;
;                     const int nscan = 16 + 256;
;                     for (int T = bid; T < nscan + 388 * 4; T += G) {
.LBB0_1599:
	s_or_b64 exec, exec, s[4:5]
	v_readlane_b32 s4, v254, 30
	v_readlane_b32 s12, v254, 3
	v_readlane_b32 s5, v254, 31
	v_readlane_b32 s13, v254, 4
	v_mov_b32_e32 v0, v236
	s_and_b64 vcc, exec, s[4:5]
	s_waitcnt lgkmcnt(0)
	s_barrier
	s_cbranch_vccz .LBB0_1650
	v_ashrrev_i32_e32 v5, 6, v0
	s_movk_i32 s1, 0x1800
	v_mul_lo_u32 v186, v5, s1
	v_readlane_b32 s1, v255, 14
	v_readlane_b32 s4, v255, 17
	s_mov_b32 s24, s4
	s_mov_b32 s101, 0
	v_add_u32_e32 v187, s1, v5
	v_lshlrev_b32_e32 v188, 4, v187
	v_lshlrev_b32_e32 v189, 7, v187
	v_readlane_b32 s5, v255, 18
	s_branch .LBB0_1603

; #define STAGE(P, BASE, LD, br, kt) do { const long _g = (long)(br) * (LD) + (long)(kt) * 64; \
;     _Pragma("unroll") for (int _i = 0; _i < 2; ++_i) { const int _b = tid * 16 + _i * 8192; int _r, _c; stage_rc(_b, _r, _c); \
;       __builtin_amdgcn_global_load_lds((const G_AS1 unsigned*)((BASE) + _g + (long)_r * (LD) + _c), \
;         (LAS unsigned*)((char*)(P) + _b), 16, 0, 0); } } while (0)
; #define BAR __builtin_amdgcn_s_barrier()
; __device__ __forceinline__ void gemm256(const bf16_t* __restrict__ A, long lda, const bf16_t* __restrict__ Bt, long ldb, int K,
;                                         int brow, int bcol, char* smem, f32x4 (&acc)[2][2][4][2]) {
;     ...
;     const int wid = tid >> 6, lane = tid & 63, wr = wid >> 2, wc = wid & 3, fr = lane & 15, fq = lane >> 4;
; #pragma unroll
;     for (int ai = 0; ai < 2; ++ai)
; #pragma unroll
;         for (int bj = 0; bj < 2; ++bj)
; #pragma unroll
;             for (int m = 0; m < 4; ++m)
; #pragma unroll
;                 for (int n = 0; n < 2; ++n) acc[ai][bj][m][n] = (f32x4){0.f, 0.f, 0.f, 0.f};
;     bf16x8 At[4][2], B0[2][2], B1[2][2];
;     const int nt = K / 64;
;     __syncthreads();
;     STAGE(SB(0, 0), Bt, ldb, bcol, 0); STAGE(SA(0, 0), A, lda, brow, 0);
;     STAGE(SB(0, 1), Bt, ldb, bcol + 128, 0); STAGE(SA(0, 1), A, lda, brow + 128, 0);
;     if (wr == 1) BAR;
; __global__ void __launch_bounds__(NTHR, 2) fwd_megakernel(Params p0) {
;     ...
;                     for (int T = bid; T < nscan + 388 * 4; T += G) {
;                         if (T < 16) { __syncthreads(); scan_task(p, jl, 4096 + T * 8 + wave, wl); __syncthreads(); }
;                         else if (T < nscan) { __syncthreads(); scan_fused(p, jl, (T - 16) * 8 + wave, wl); __syncthreads(); }
;                         else { int pm, pn; tile_map256(T - nscan, 388, 4, pm, pn); t256_kvup(p, pm, pn, smem); }
.LBB0_1602:
	v_readlane_b32 s4, v255, 21
	v_readlane_b32 s5, v255, 22
	v_readlane_b32 s6, v255, 23
	v_readlane_b32 s1, v255, 15
	s_add_i32 s24, s24, s6
	v_readlane_b32 s4, v254, 36
	v_add_u32_e32 v188, s1, v188
	v_readlane_b32 s1, v255, 16
	s_cmpk_gt_i32 s24, 0x71f
	v_add_u32_e32 v187, s4, v187
	v_add_u32_e32 v189, s1, v189
	v_readlane_b32 s7, v255, 24
	v_readlane_b32 s5, v254, 37
	s_cmpk_eq_u32 s6, 0x100
	s_cbranch_scc1 .Lmy_sc_g256
	s_cmpk_gt_i32 s24, 0x71f
	s_cbranch_scc1 .LBB0_1650
	s_branch .Lmy_sc_cont
.Lmy_sc_g256:
	v_readlane_b32 s100, v255, 17
	s_cmp_eq_u32 s101, 1
	s_cbranch_scc1 .LBB0_1650
	s_cmp_lt_u32 s100, 16
	s_cbranch_scc0 .Lmy_sc_notlow
	s_cmpk_ge_i32 s24, 0x200
	s_cbranch_scc1 .LBB0_1650
	s_branch .Lmy_sc_cont
.Lmy_sc_notlow:
	s_cmpk_gt_i32 s24, 0x71f
	s_cbranch_scc0 .Lmy_sc_cont
	s_sub_u32 s100, s100, 32
	s_cmp_lt_u32 s100, 0x60
	s_cbranch_scc0 .LBB0_1650
	s_and_b32 s24, s100, 15
	s_lshr_b32 s100, s100, 4
	s_add_u32 s100, s100, 2
	s_lshl_b32 s100, s100, 8
	s_add_u32 s24, s24, s100
	s_mov_b32 s101, 1
.Lmy_sc_cont:
.LBB0_1603:
	s_cmp_gt_i32 s24, 15
	s_mov_b64 s[4:5], -1
	s_cbranch_scc0 .LBB0_1625
	s_cmpk_gt_u32 s24, 0x10f
	s_cbranch_scc0 .LBB0_1614
	s_and_b32 s1, s24, 7
	s_add_i32 s4, s24, 0xfef0
	s_mulk_i32 s1, 0xc2
	s_bfe_u32 s4, s4, 0xd0003
	s_add_i32 s4, s4, s1
	s_lshr_b32 s1, s4, 2
	s_and_b32 s14, s1, 0xffc
	s_sub_i32 s1, 0x184, s14
	s_min_u32 s1, s1, 4
	v_cvt_f32_ubyte0_e32 v0, s1
	v_rcp_iflag_f32_e32 v2, v0
	s_and_b32 s6, s4, 15
	v_cvt_f32_ubyte0_e32 v3, s6
	v_mul_f32_e32 v2, v3, v2
	v_trunc_f32_e32 v2, v2
	v_cvt_u32_f32_e32 v6, v2
	v_fma_f32 v2, -v2, v0, v3
	v_cmp_ge_f32_e64 s[4:5], |v2|, v0
	s_cmp_lg_u64 s[4:5], 0
	v_readfirstlane_b32 s7, v6
	s_addc_u32 s4, s7, 0
	s_mul_i32 s1, s4, s1
	s_sub_i32 s1, s6, s1
	s_and_b32 s1, s1, 0xff
	v_mov_b32_e32 v0, v236
	s_add_i32 s14, s14, s1
	s_and_b32 s1, s4, 0xff
	s_load_dwordx2 s[4:5], s[12:13], 0x130
	s_lshl_b32 s6, s1, 17
	v_bfe_i32 v3, v0, 27, 1
	v_lshlrev_b32_e32 v22, 4, v0
	v_lshrrev_b32_e32 v3, 22, v3
	v_add_u32_e32 v3, v22, v3
	v_and_b32_e32 v3, 0xfffffc00, v3
	v_ashrrev_i32_e32 v2, 31, v0
	v_sub_u32_e32 v3, v22, v3
	v_lshrrev_b32_e32 v2, 26, v2
	v_lshrrev_b32_e32 v6, 4, v3
	v_add_u32_e32 v2, v0, v2
	v_bitop3_b32 v6, v6, v3, 32 bitop3:0x6c
	v_ashrrev_i32_e32 v3, 31, v3
	v_ashrrev_i32_e32 v2, 6, v2
	v_lshrrev_b32_e32 v3, 26, v3
	v_lshlrev_b32_e32 v7, 3, v2
	v_add_u32_e32 v3, v6, v3
	v_and_b32_e32 v7, -16, v7
	v_ashrrev_i32_e32 v3, 6, v3
	v_add_u32_e32 v14, v3, v7
	v_mul_i32_i24_e32 v3, 64, v3
	s_waitcnt lgkmcnt(0)
	s_add_u32 s10, s4, s6
	v_lshlrev_b32_e32 v2, 5, v2
	v_sub_u32_e32 v3, v6, v3
	s_addc_u32 s11, s5, 0
	v_and_b32_e32 v2, 32, v2
	v_ashrrev_i16_sdwa v3, v240, sext(v3) dst_sel:DWORD dst_unused:UNUSED_PAD src0_sel:DWORD src1_sel:BYTE_0
	s_add_u32 s6, s10, 0x2eac000
	v_add_u32_sdwa v2, v2, sext(v3) dst_sel:DWORD dst_unused:UNUSED_PAD src0_sel:DWORD src1_sel:WORD_0
	v_ashrrev_i32_e32 v15, 31, v14
	s_addc_u32 s7, s11, 0
	v_lshlrev_b64 v[20:21], 9, v[14:15]
	v_ashrrev_i32_e32 v3, 31, v2
	v_lshl_add_u64 v[6:7], s[6:7], 0, v[20:21]
	v_lshlrev_b64 v[2:3], 1, v[2:3]
	s_waitcnt vmcnt(0)
	v_add_u32_e32 v25, 0x2000, v22
	v_lshl_add_u64 v[8:9], v[6:7], 0, v[2:3]
	v_ashrrev_i32_e32 v6, 31, v25
	v_lshrrev_b32_e32 v6, 22, v6
	v_add_u32_e32 v6, v25, v6
	v_ashrrev_i32_e32 v6, 10, v6
	v_mul_i32_i24_e32 v7, 0x400, v6
	v_sub_u32_e32 v7, v25, v7
	v_lshrrev_b32_e32 v10, 4, v7
	v_bitop3_b32 v7, v10, v7, 32 bitop3:0x6c
	v_add_u32_e32 v28, 0x10000, v22
	v_ashrrev_i32_e32 v11, 31, v7
	v_readfirstlane_b32 s8, v28
	v_lshrrev_b32_e32 v11, 26, v11
	v_add_u32_e32 v29, 0x12000, v22
	s_mov_b32 m0, s8
	v_lshlrev_b32_e32 v10, 3, v6
	v_add_u32_e32 v11, v7, v11
	v_readfirstlane_b32 s8, v29
	s_barrier
	global_load_lds_dwordx4 v[8:9], off
	v_and_b32_e32 v10, -16, v10
	v_ashrrev_i32_e32 v12, 6, v11
	s_mov_b32 m0, s8
	s_lshl_b32 s8, s14, 17
	v_add_u32_e32 v16, v12, v10
	v_and_b32_e32 v10, 0xc0, v11
	s_add_u32 s15, s4, s8
	v_lshlrev_b32_e32 v6, 5, v6
	v_sub_u32_e32 v7, v7, v10
	s_addc_u32 s16, s5, 0
	v_and_b32_e32 v6, 32, v6
	v_ashrrev_i16_sdwa v7, v240, sext(v7) dst_sel:DWORD dst_unused:UNUSED_PAD src0_sel:DWORD src1_sel:BYTE_0
	s_add_u32 s8, s15, 0x17e6c000
	v_add_u32_sdwa v6, v6, sext(v7) dst_sel:DWORD dst_unused:UNUSED_PAD src0_sel:DWORD src1_sel:WORD_0
	v_ashrrev_i32_e32 v17, 31, v16
	s_addc_u32 s9, s16, 0
	v_lshlrev_b64 v[30:31], 9, v[16:17]
	v_ashrrev_i32_e32 v7, 31, v6
	s_add_u32 s10, s10, 0x2ebc000
	v_lshl_add_u64 v[10:11], s[6:7], 0, v[30:31]
	v_lshlrev_b64 v[6:7], 1, v[6:7]
	s_addc_u32 s11, s11, 0
	v_lshl_add_u64 v[18:19], v[10:11], 0, v[6:7]
	v_lshl_add_u64 v[10:11], s[8:9], 0, v[20:21]
	v_readfirstlane_b32 s17, v22
	v_lshl_add_u64 v[26:27], s[10:11], 0, v[20:21]
	global_load_lds_dwordx4 v[18:19], off
	v_lshl_add_u64 v[10:11], v[10:11], 0, v[2:3]
	s_mov_b32 m0, s17
	v_lshl_add_u64 v[12:13], s[8:9], 0, v[30:31]
	v_readfirstlane_b32 s17, v25
	v_lshl_add_u64 v[32:33], v[26:27], 0, v[2:3]
	v_add_u32_e32 v26, 0x14000, v22
	global_load_lds_dwordx4 v[10:11], off
	v_lshl_add_u64 v[12:13], v[12:13], 0, v[6:7]
	s_mov_b32 m0, s17
	v_readfirstlane_b32 s17, v26
	global_load_lds_dwordx4 v[12:13], off
	s_mov_b32 m0, s17
	v_add_u32_e32 v27, 0x16000, v22
	global_load_lds_dwordx4 v[32:33], off
	v_lshl_add_u64 v[32:33], s[10:11], 0, v[30:31]
	v_readfirstlane_b32 s10, v27
	s_mov_b32 m0, s10
	s_add_u32 s10, s15, 0x17e7c000
	s_addc_u32 s11, s16, 0
	v_add_u32_e32 v23, 0x4000, v22
	v_lshl_add_u64 v[32:33], v[32:33], 0, v[6:7]
	v_lshl_add_u64 v[20:21], s[10:11], 0, v[20:21]
	v_readfirstlane_b32 s15, v23
	global_load_lds_dwordx4 v[32:33], off
	v_lshl_add_u64 v[20:21], v[20:21], 0, v[2:3]
	s_mov_b32 m0, s15
	v_add_u32_e32 v24, 0x6000, v22
	global_load_lds_dwordx4 v[20:21], off
	v_lshl_add_u64 v[20:21], s[10:11], 0, v[30:31]
	v_readfirstlane_b32 s10, v24
	v_lshl_add_u64 v[20:21], v[20:21], 0, v[6:7]
	s_mov_b32 m0, s10
	s_nop 0
	global_load_lds_dwordx4 v[20:21], off
	v_ashrrev_i32_e32 v20, 8, v0
	v_cmp_eq_u32_e32 vcc, 1, v20
	s_and_saveexec_b64 s[10:11], vcc
	s_cbranch_execz .LBB0_1607
	s_barrier

; __global__ void __launch_bounds__(NTHR, 2) fwd_megakernel(Params p0) {
;     cg::grid_group grid = cg::this_grid();
;     __shared__ __attribute__((aligned(16))) char smem[SMEM_BYTES];
	.amdhsa_kernel _Z14fwd_megakernel6Params
		.amdhsa_group_segment_fixed_size 131088
		.amdhsa_private_segment_fixed_size 0
		.amdhsa_kernarg_size 568
		.amdhsa_user_sgpr_count 2
		.amdhsa_user_sgpr_dispatch_ptr 0
		.amdhsa_user_sgpr_queue_ptr 0
		.amdhsa_user_sgpr_kernarg_segment_ptr 1
		.amdhsa_user_sgpr_dispatch_id 0
		.amdhsa_user_sgpr_kernarg_preload_length 0
		.amdhsa_user_sgpr_kernarg_preload_offset 0
		.amdhsa_user_sgpr_private_segment_size 0
		.amdhsa_uses_dynamic_stack 0
		.amdhsa_enable_private_segment 0
		.amdhsa_system_sgpr_workgroup_id_x 1
		.amdhsa_system_sgpr_workgroup_id_y 0
		.amdhsa_system_sgpr_workgroup_id_z 0
		.amdhsa_system_sgpr_workgroup_info 0
		.amdhsa_system_vgpr_workitem_id 2
		.amdhsa_next_free_vgpr 256
		.amdhsa_next_free_sgpr 102
		.amdhsa_accum_offset 256
		.amdhsa_reserve_vcc 1
		.amdhsa_float_round_mode_32 0
		.amdhsa_float_round_mode_16_64 0
		.amdhsa_float_denorm_mode_32 3
		.amdhsa_float_denorm_mode_16_64 3
		.amdhsa_dx10_clamp 1
		.amdhsa_ieee_mode 1
		.amdhsa_fp16_overflow 0
		.amdhsa_tg_split 0
		.amdhsa_exception_fp_ieee_invalid_op 0
		.amdhsa_exception_fp_denorm_src 0
		.amdhsa_exception_fp_ieee_div_zero 0
		.amdhsa_exception_fp_ieee_overflow 0
		.amdhsa_exception_fp_ieee_underflow 0
		.amdhsa_exception_fp_ieee_inexact 0
		.amdhsa_exception_int_div_zero 0
	.end_amdhsa_kernel

; __global__ void __launch_bounds__(NTHR, 2) fwd_megakernel(Params p0) {
;     cg::grid_group grid = cg::this_grid();
;     __shared__ __attribute__((aligned(16))) char smem[SMEM_BYTES];
amdhsa.kernels:
  - .agpr_count:     0
    .args:
      - .offset:         0
        .size:           312
        .value_kind:     by_value
      - .offset:         312
        .size:           4
        .value_kind:     hidden_block_count_x
      - .offset:         316
        .size:           4
        .value_kind:     hidden_block_count_y
      - .offset:         320
        .size:           4
        .value_kind:     hidden_block_count_z
      - .offset:         324
        .size:           2
        .value_kind:     hidden_group_size_x
      - .offset:         326
        .size:           2
        .value_kind:     hidden_group_size_y
      - .offset:         328
        .size:           2
        .value_kind:     hidden_group_size_z
      - .offset:         330
        .size:           2
        .value_kind:     hidden_remainder_x
      - .offset:         332
        .size:           2
        .value_kind:     hidden_remainder_y
      - .offset:         334
        .size:           2
        .value_kind:     hidden_remainder_z
      - .offset:         352
        .size:           8
        .value_kind:     hidden_global_offset_x
      - .offset:         360
        .size:           8
        .value_kind:     hidden_global_offset_y
      - .offset:         368
        .size:           8
        .value_kind:     hidden_global_offset_z
      - .offset:         376
        .size:           2
        .value_kind:     hidden_grid_dims
      - .offset:         400
        .size:           8
        .value_kind:     hidden_multigrid_sync_arg
    .group_segment_fixed_size: 131088
    .kernarg_segment_align: 8
    .kernarg_segment_size: 568
    .language:       OpenCL C
    .language_version:
      - 2
      - 0
    .max_flat_workgroup_size: 512
    .name:           _Z14fwd_megakernel6Params
    .private_segment_fixed_size: 0
    .sgpr_count:     108
    .sgpr_spill_count: 131
    .symbol:         _Z14fwd_megakernel6Params.kd
    .uniform_work_group_size: 1
    .uses_dynamic_stack: false
    .vgpr_count:     256
    .vgpr_spill_count: 0
    .wavefront_size: 64
